# combination: per-wave tile skip + packed pending-P copies + P4 rstd prefetch + P6 epilogue load hoist on top of v063
# speedup vs baseline: 1.0073x; 1.0073x over previous
; template <class Epi, class Sched, bool ALIGN_EPI = false, bool SP2 = false>
; __device__ __forceinline__ void gemm_phase(PG8_LAS unsigned char* lds, const Gemm g, const Sched& S, const Epi& E, const int wave_) {
;     ...
;         for (int a = 0; a < 2; ++a)
; #pragma unroll
;             for (int b = 0; b < 2; ++b)
; #pragma unroll
;                 for (int m = 0; m < 4; ++m)
; #pragma unroll
;                     for (int n = 0; n < 2; ++n) acc[a][b][m][n] = (f32x4){0.f, 0.f, 0.f, 0.f};
;         cur = nxt; cA = nA; cB = nB; ++ui;
;     __device__ __forceinline__ void operator()(const f32x4 (&acc)[2][2][4][2], const Unit& u, int wr, int wc, int fr, int fq) const {
;     ...
;             for (int m = 0; m < 4; ++m) ssr[ai][m] = hss[row0 + ai * HALF + m * 16];
.LBB0_494:
	v_lshl_add_u32 v244, s4, 8, v153
	v_ashrrev_i32_e32 v245, 31, v244
	v_lshl_add_u64 v[246:247], v[244:245], 2, s[8:9]
	global_load_dword v236, v[246:247], off
	global_load_dword v237, v[246:247], off offset:64
	global_load_dword v238, v[246:247], off offset:128
	global_load_dword v239, v[246:247], off offset:192
	global_load_dword v240, v[246:247], off offset:512
	global_load_dword v241, v[246:247], off offset:576
	global_load_dword v242, v[246:247], off offset:640
	global_load_dword v243, v[246:247], off offset:704
	s_ashr_i32 s29, s28, 31
	s_lshl_b64 s[30:31], s[28:29], 20
	s_add_u32 s30, s38, s30
	s_addc_u32 s31, s39, s31
	s_and_b64 s[34:35], s[0:1], exec
	s_cselect_b32 s5, s31, s37
	s_cselect_b32 s7, s30, s36
	s_ashr_i32 s27, s26, 31
	s_lshl_b64 s[34:35], s[26:27], 20
	v_readlane_b32 s42, v248, 31
	v_readlane_b32 s43, v248, 32
	s_add_u32 s34, s42, s34
	s_addc_u32 s35, s43, s35
	s_and_b64 s[42:43], s[0:1], exec
	s_cselect_b32 s27, s35, s41
	s_cselect_b32 s29, s34, s40
	s_add_u32 s36, s36, 0x80080
	s_addc_u32 s37, s37, 0
	s_add_u32 s61, s40, 0x100
	v_mov_b32_e32 v0, 0
	s_addc_u32 s62, s41, 0
	s_mov_b32 s63, -2
	v_mov_b32_e32 v1, 0
	v_mov_b64_e32 v[2:3], 0
	v_mov_b64_e32 v[4:5], 0
	v_mov_b64_e32 v[6:7], 0
	v_mov_b64_e32 v[8:9], 0
	v_mov_b64_e32 v[10:11], 0
	v_mov_b64_e32 v[12:13], 0
	v_mov_b64_e32 v[14:15], 0
	v_mov_b64_e32 v[16:17], 0
	v_mov_b64_e32 v[18:19], 0
	v_mov_b64_e32 v[20:21], 0
	v_mov_b64_e32 v[22:23], 0
	v_mov_b64_e32 v[24:25], 0
	v_mov_b64_e32 v[26:27], 0
	v_mov_b64_e32 v[28:29], 0
	v_mov_b64_e32 v[30:31], 0
	v_mov_b64_e32 v[32:33], 0
	v_mov_b64_e32 v[34:35], 0
	v_mov_b64_e32 v[36:37], 0
	v_mov_b64_e32 v[38:39], 0
	v_mov_b64_e32 v[40:41], 0
	v_mov_b64_e32 v[42:43], 0
	v_mov_b64_e32 v[44:45], 0
	v_mov_b64_e32 v[46:47], 0
	v_mov_b64_e32 v[48:49], 0
	v_mov_b64_e32 v[50:51], 0
	v_mov_b64_e32 v[52:53], 0
	v_mov_b64_e32 v[54:55], 0
	v_mov_b64_e32 v[56:57], 0
	v_mov_b64_e32 v[58:59], 0
	v_mov_b64_e32 v[60:61], 0
	v_mov_b64_e32 v[62:63], 0
	v_mov_b64_e32 v[64:65], 0
	v_mov_b64_e32 v[66:67], 0
	v_mov_b64_e32 v[68:69], 0
	v_mov_b64_e32 v[70:71], 0
	v_mov_b64_e32 v[72:73], 0
	v_mov_b64_e32 v[74:75], 0
	v_mov_b64_e32 v[76:77], 0
	v_mov_b64_e32 v[78:79], 0
	v_mov_b64_e32 v[80:81], 0
	v_mov_b64_e32 v[82:83], 0
	v_mov_b64_e32 v[84:85], 0
	v_mov_b64_e32 v[86:87], 0
	v_mov_b64_e32 v[88:89], 0
	v_mov_b64_e32 v[90:91], 0
	v_mov_b64_e32 v[92:93], 0
	v_mov_b64_e32 v[94:95], 0
	v_mov_b64_e32 v[96:97], 0
	v_mov_b64_e32 v[98:99], 0
	v_mov_b64_e32 v[100:101], 0
	v_mov_b64_e32 v[102:103], 0
	v_mov_b64_e32 v[104:105], 0
	v_mov_b64_e32 v[106:107], 0
	v_mov_b64_e32 v[108:109], 0
	v_mov_b64_e32 v[110:111], 0
	v_mov_b64_e32 v[112:113], 0
	v_mov_b64_e32 v[114:115], 0
	v_mov_b64_e32 v[116:117], 0
	v_mov_b64_e32 v[118:119], 0
	v_mov_b64_e32 v[120:121], 0
	v_mov_b64_e32 v[122:123], 0
	v_mov_b64_e32 v[124:125], 0
	v_mov_b64_e32 v[126:127], 0

; __device__ __forceinline__ unsigned pk_bf16(float lo, float hi) { return pg8::cvt_pk_bf16(lo, hi); }
; template <bool DO_PV> ...
;     ...
;     for (int s = 0; s < 4; ++s) { const int ph = s >> 1, rb = 8 * (s & 1);
;         u32x4 w; w.x = pk_bf16(p[ph][rb], p[ph][rb + 1]); w.y = pk_bf16(p[ph][rb + 2], p[ph][rb + 3]); w.z = pk_bf16(p[ph][rb + 4], p[ph][rb + 5]); w.w = pk_bf16(p[ph][rb + 6], p[ph][rb + 7]);
;         pa[s] = __builtin_bit_cast(bf16x8, w); }
; __device__ __forceinline__ void attn_unit(LAS unsigned char* lds, const int wid, int b, int h, int qb, const bf16_t* __restrict__ Q, const bf16_t* __restrict__ K,
;                                           const bf16_t* __restrict__ V, const bf16_t* __restrict__ ZS, bf16_t* __restrict__ OG) {
;     ...
;             if (prev_valid) attn_tile<true>(kb, vbp, qf, o, pa, carry, koff, vbase, vcq, k0, qw0, qabs, hi);
;             else            attn_tile<false>(kb, vbp, qf, o, pa, carry, koff, vbase, vcq, k0, qw0, qabs, hi);
;         }
;         prev_valid = valid;
.LBB0_607:
	v_mov_b32_e32 v158, v159
	v_pk_mov_b32 v[140:141], v[64:65], v[64:65] op_sel:[0,1]
	v_pk_mov_b32 v[142:143], v[66:67], v[66:67] op_sel:[0,1]
	v_pk_mov_b32 v[136:137], v[68:69], v[68:69] op_sel:[0,1]
	v_pk_mov_b32 v[138:139], v[70:71], v[70:71] op_sel:[0,1]
	v_pk_mov_b32 v[132:133], v[72:73], v[72:73] op_sel:[0,1]
	v_pk_mov_b32 v[134:135], v[74:75], v[74:75] op_sel:[0,1]
	v_pk_mov_b32 v[128:129], v[76:77], v[76:77] op_sel:[0,1]
	v_pk_mov_b32 v[130:131], v[78:79], v[78:79] op_sel:[0,1]
	s_branch .LBB0_609
